# v69 + filter MLP layer-1 weights (33) also preloaded once per wave, its 3x11 loop unrolled
# baseline (speedup 1.0000x reference)
; #define GAS __attribute__((address_space(1)))
; __device__ __forceinline__ void pro_a(Frame& F, CArgs a, unsigned long long& tm_acc) {
;     ...
;         if (F.blk < DEPTH * 36) {
;             const int it = F.blk; const int l = it / 36, grp = it % 36; const bool isc = grp >= 32; const int L = isc ? CTXL : SEQ, p0 = (isc ? grp - 32 : grp) * 64;
;             __syncthreads();
;             { int _t = F.tid; asm volatile("" : "+v"(_t)); F.tid = _t; F.lane = _t & 63; F.wave = __builtin_amdgcn_readfirstlane(_t >> 6); }
;             for (int pp = 0; pp < 8; ++pp) {
;                 const int pos = p0 + F.wave * 8 + pp;
;                 const float t = (float)pos / (float)(L - 1);
;                 const float w = 6.2831853071795862f * (float)pos / (float)L;
;                 float zf = 0.f;
;                 if (F.lane == 0) zf = t;
;                 else if (F.lane < 33) { const int bi = (F.lane - 1) & 15; const float f = 1e-4f + (float)bi * ((15.0f - 1e-4f) / 15.0f); const float ang = f * w; zf = F.lane <= 16 ? cosf(ang) : -sinf(ang); }
;                 float h = ((const GAS float*)a->in[I_FB1])[l * 64 + F.lane];
;                 for (int i = 0; i < 33; ++i) h += __shfl(zf, i) * ((const GAS float*)a->in[I_FW1])[((size_t)l * 33 + i) * 64 + F.lane];
;                 h = sinf(((const GAS float*)a->in[I_FF1])[l * 64 + F.lane] * h);
;                 float h2 = ((const GAS float*)a->in[I_FB2])[l * 64 + F.lane];
;                 for (int i = 0; i < 64; ++i) h2 += __shfl(h, i) * ((const GAS float*)a->in[I_FW2])[((size_t)l * 64 + i) * 64 + F.lane];
.LBB0_207:
	s_or_b64 exec, exec, s[4:5]
	s_cmpk_lt_i32 s2, 0x90
	s_cbranch_scc0 .LBB0_270
	s_mul_hi_i32 s4, s2, 0x38e38e39
	s_lshr_b32 s5, s4, 31
	s_ashr_i32 s4, s4, 3
	s_barrier
	s_load_dwordx16 s[12:27], s[0:1], 0x60
	s_add_i32 s38, s4, s5
	s_waitcnt vmcnt(22)
	v_and_b32_e32 v6, 63, v0
	v_lshl_or_b32 v2, s38, 6, v6
	v_ashrrev_i32_e32 v3, 31, v2
	v_lshlrev_b64 v[2:3], 2, v[2:3]
	s_load_dwordx2 s[4:5], s[0:1], 0xa0
	s_waitcnt lgkmcnt(0)
	v_lshl_add_u64 v[4:5], s[14:15], 0, v[2:3]
	global_load_dword v12, v[4:5], off
	v_lshl_add_u64 v[4:5], s[16:17], 0, v[2:3]
	global_load_dword v13, v[4:5], off
	v_lshl_add_u64 v[4:5], s[20:21], 0, v[2:3]
	global_load_dword v14, v[4:5], off
	v_lshl_add_u64 v[4:5], s[22:23], 0, v[2:3]
	global_load_dword v15, v[4:5], off
	v_lshl_add_u64 v[4:5], s[26:27], 0, v[2:3]
	v_lshl_add_u64 v[2:3], s[4:5], 0, v[2:3]
	global_load_dword v16, v[4:5], off
	global_load_dword v17, v[2:3], off
	s_mul_i32 s4, s38, 36
	s_sub_i32 s4, s2, s4
	s_lshl_b32 s6, s4, 6
	s_add_i32 s7, s6, 0xfffff800
	s_cmp_gt_i32 s4, 31
	s_cselect_b64 s[16:17], -1, 0
	s_movk_i32 s8, 0x100
	s_and_b64 s[4:5], s[16:17], exec
	s_cselect_b32 s44, s8, 0x800
	s_cselect_b32 s45, s7, s6
	s_add_i32 s4, s44, -1
	v_cvt_f32_u32_e32 v1, s4
	v_readfirstlane_b32 s4, v0
	s_ashr_i32 s6, s4, 6
	s_ashr_i32 s39, s38, 31
	s_lshl_b32 s46, s6, 3
	v_mbcnt_lo_u32_b32 v2, -1, 0
	s_lshl_b32 s6, s6, 11
	s_lshl_b64 s[10:11], s[38:39], 14
	s_add_i32 s46, s46, s45
	v_mbcnt_hi_u32_b32 v3, -1, v2
	s_add_i32 s6, s6, 0
	v_add_u32_e32 v4, -1, v0
	s_mul_i32 s15, s38, 0x2100
	v_and_b32_e32 v4, 15, v4
	v_lshlrev_b32_e32 v3, 2, v3
	s_mul_hi_i32 s14, s38, 0x2100
	s_add_u32 s12, s12, s15
	s_waitcnt vmcnt(25)
	v_cvt_f32_u32_e32 v18, s44
	v_lshlrev_b32_e32 v2, 2, v6
	v_cvt_f32_ubyte0_e32 v4, v4
	v_mov_b32_e32 v20, 0x38d1b717
	v_and_b32_e32 v21, 0x100, v3
	v_mov_b32_e32 v3, 0
	s_addc_u32 s13, s13, s14
	v_add_u32_e32 v19, s6, v2
	v_fmac_f32_e32 v20, 0x3f7fff90, v4
	v_lshl_add_u64 v[4:5], s[12:13], 0, v[2:3]
	v_or_b32_e32 v2, s10, v2
	s_mov_b64 s[12:13], 0xa00
	v_or_b32_e32 v8, 0x700, v2
	v_mov_b32_e32 v9, s11
	s_mov_b32 s47, 0
	v_cmp_ne_u32_e64 s[4:5], 0, v6
	v_cmp_gt_u32_e64 s[6:7], 33, v6
	v_cmp_lt_u32_e64 s[8:9], 16, v6
	v_lshl_add_u64 v[4:5], v[4:5], 0, s[12:13]
	v_lshl_add_u64 v[6:7], s[18:19], 0, v[8:9]
	v_lshl_add_u64 v[8:9], s[24:25], 0, v[8:9]
	s_brev_b32 s48, 18
	s_mov_b32 s49, 0xfe5163ab
	s_mov_b32 s50, 0x3c439041
	s_mov_b32 s51, 0xdb629599
	s_mov_b32 s52, 0xf534ddc0
	s_mov_b32 s53, 0xfc2757d1
	s_mov_b32 s54, 0x4e441529
	s_mov_b32 s55, 0xa2f9836e
	s_mov_b32 s56, 0x3fc90fda
	s_mov_b32 s57, 0x3f22f983
	s_mov_b32 s58, 0xbfc90fda
	s_waitcnt vmcnt(24)
	v_mov_b32_e32 v22, 0x3c0881c4
	v_mov_b32_e32 v23, 0xbab64f3b
	s_brev_b32 s59, 1
	s_movk_i32 s60, 0x1f8
	s_mov_b64 s[18:19], 0xb00
	s_mov_b64 s[20:21], 0x800
	v_not_b32_e32 v24, 63
	v_not_b32_e32 v25, 31
	s_waitcnt vmcnt(23)
	v_mov_b32_e32 v26, 0xffc00000
	v_mov_b32_e32 v27, 0x7fc00000
	v_mov_b64_e32 v[10:11], v[6:7]
	global_load_dword v102, v[10:11], off offset:-1792
	global_load_dword v103, v[10:11], off offset:-1536
	global_load_dword v104, v[10:11], off offset:-1280
	global_load_dword v105, v[10:11], off offset:-1024
	global_load_dword v106, v[10:11], off offset:-768
	global_load_dword v107, v[10:11], off offset:-512
	global_load_dword v108, v[10:11], off offset:-256
	global_load_dword v109, v[10:11], off
	v_lshl_add_u64 v[10:11], v[10:11], 0, s[20:21]
	global_load_dword v110, v[10:11], off offset:-1792
	global_load_dword v111, v[10:11], off offset:-1536
	global_load_dword v112, v[10:11], off offset:-1280
	global_load_dword v113, v[10:11], off offset:-1024
	global_load_dword v114, v[10:11], off offset:-768
	global_load_dword v115, v[10:11], off offset:-512
	global_load_dword v116, v[10:11], off offset:-256
	global_load_dword v117, v[10:11], off
	v_lshl_add_u64 v[10:11], v[10:11], 0, s[20:21]
	global_load_dword v118, v[10:11], off offset:-1792
	global_load_dword v119, v[10:11], off offset:-1536
	global_load_dword v120, v[10:11], off offset:-1280
	global_load_dword v121, v[10:11], off offset:-1024
	global_load_dword v122, v[10:11], off offset:-768
	global_load_dword v123, v[10:11], off offset:-512
	global_load_dword v124, v[10:11], off offset:-256
	global_load_dword v125, v[10:11], off
	v_lshl_add_u64 v[10:11], v[10:11], 0, s[20:21]
	global_load_dword v126, v[10:11], off offset:-1792
	global_load_dword v127, v[10:11], off offset:-1536
	global_load_dword v128, v[10:11], off offset:-1280
	global_load_dword v129, v[10:11], off offset:-1024
	global_load_dword v130, v[10:11], off offset:-768
	global_load_dword v131, v[10:11], off offset:-512
	global_load_dword v132, v[10:11], off offset:-256
	global_load_dword v133, v[10:11], off
	v_lshl_add_u64 v[10:11], v[10:11], 0, s[20:21]
	global_load_dword v134, v[10:11], off offset:-1792
	global_load_dword v135, v[10:11], off offset:-1536
	global_load_dword v136, v[10:11], off offset:-1280
	global_load_dword v137, v[10:11], off offset:-1024
	global_load_dword v138, v[10:11], off offset:-768
	global_load_dword v139, v[10:11], off offset:-512
	global_load_dword v140, v[10:11], off offset:-256
	global_load_dword v141, v[10:11], off
	v_lshl_add_u64 v[10:11], v[10:11], 0, s[20:21]
	global_load_dword v142, v[10:11], off offset:-1792
	global_load_dword v143, v[10:11], off offset:-1536
	global_load_dword v144, v[10:11], off offset:-1280
	global_load_dword v145, v[10:11], off offset:-1024
	global_load_dword v146, v[10:11], off offset:-768
	global_load_dword v147, v[10:11], off offset:-512
	global_load_dword v148, v[10:11], off offset:-256
	global_load_dword v149, v[10:11], off
	v_lshl_add_u64 v[10:11], v[10:11], 0, s[20:21]
; #define GAS __attribute__((address_space(1)))
; __device__ __forceinline__ void pro_a(Frame& F, CArgs a, unsigned long long& tm_acc) {
;     ...
;                 float h = ((const GAS float*)a->in[I_FB1])[l * 64 + F.lane];
;                 for (int i = 0; i < 33; ++i) h += __shfl(zf, i) * ((const GAS float*)a->in[I_FW1])[((size_t)l * 33 + i) * 64 + F.lane];
;                 h = sinf(((const GAS float*)a->in[I_FF1])[l * 64 + F.lane] * h);
;                 float h2 = ((const GAS float*)a->in[I_FB2])[l * 64 + F.lane];
;                 for (int i = 0; i < 64; ++i) h2 += __shfl(h, i) * ((const GAS float*)a->in[I_FW2])[((size_t)l * 64 + i) * 64 + F.lane];
;                 h2 = sinf(((const GAS float*)a->in[I_FF2])[l * 64 + F.lane] * h2);
;                 float h3 = ((const GAS float*)a->in[I_FB3])[l * 64 + F.lane];
;                 for (int i = 0; i < 64; ++i) h3 += __shfl(h2, i) * ((const GAS float*)a->in[I_FW3])[((size_t)l * 64 + i) * 64 + F.lane];
	global_load_dword v150, v[10:11], off offset:-1792
	global_load_dword v151, v[10:11], off offset:-1536
	global_load_dword v152, v[10:11], off offset:-1280
	global_load_dword v153, v[10:11], off offset:-1024
	global_load_dword v154, v[10:11], off offset:-768
	global_load_dword v155, v[10:11], off offset:-512
	global_load_dword v156, v[10:11], off offset:-256
	global_load_dword v157, v[10:11], off
	v_lshl_add_u64 v[10:11], v[10:11], 0, s[20:21]
	global_load_dword v158, v[10:11], off offset:-1792
	global_load_dword v159, v[10:11], off offset:-1536
	global_load_dword v160, v[10:11], off offset:-1280
	global_load_dword v161, v[10:11], off offset:-1024
	global_load_dword v162, v[10:11], off offset:-768
	global_load_dword v163, v[10:11], off offset:-512
	global_load_dword v164, v[10:11], off offset:-256
	global_load_dword v165, v[10:11], off
	v_mov_b64_e32 v[10:11], v[8:9]
	global_load_dword v166, v[10:11], off offset:-1792
	global_load_dword v167, v[10:11], off offset:-1536
	global_load_dword v168, v[10:11], off offset:-1280
	global_load_dword v169, v[10:11], off offset:-1024
	global_load_dword v170, v[10:11], off offset:-768
	global_load_dword v171, v[10:11], off offset:-512
	global_load_dword v172, v[10:11], off offset:-256
	global_load_dword v173, v[10:11], off
	v_lshl_add_u64 v[10:11], v[10:11], 0, s[20:21]
	global_load_dword v174, v[10:11], off offset:-1792
	global_load_dword v175, v[10:11], off offset:-1536
	global_load_dword v176, v[10:11], off offset:-1280
	global_load_dword v177, v[10:11], off offset:-1024
	global_load_dword v178, v[10:11], off offset:-768
	global_load_dword v179, v[10:11], off offset:-512
	global_load_dword v180, v[10:11], off offset:-256
	global_load_dword v181, v[10:11], off
	v_lshl_add_u64 v[10:11], v[10:11], 0, s[20:21]
	global_load_dword v182, v[10:11], off offset:-1792
	global_load_dword v183, v[10:11], off offset:-1536
	global_load_dword v184, v[10:11], off offset:-1280
	global_load_dword v185, v[10:11], off offset:-1024
	global_load_dword v186, v[10:11], off offset:-768
	global_load_dword v187, v[10:11], off offset:-512
	global_load_dword v188, v[10:11], off offset:-256
	global_load_dword v189, v[10:11], off
	v_lshl_add_u64 v[10:11], v[10:11], 0, s[20:21]
	global_load_dword v190, v[10:11], off offset:-1792
	global_load_dword v191, v[10:11], off offset:-1536
	global_load_dword v192, v[10:11], off offset:-1280
	global_load_dword v193, v[10:11], off offset:-1024
	global_load_dword v194, v[10:11], off offset:-768
	global_load_dword v195, v[10:11], off offset:-512
	global_load_dword v196, v[10:11], off offset:-256
	global_load_dword v197, v[10:11], off
	v_lshl_add_u64 v[10:11], v[10:11], 0, s[20:21]
	global_load_dword v198, v[10:11], off offset:-1792
	global_load_dword v199, v[10:11], off offset:-1536
	global_load_dword v200, v[10:11], off offset:-1280
	global_load_dword v201, v[10:11], off offset:-1024
	global_load_dword v202, v[10:11], off offset:-768
	global_load_dword v203, v[10:11], off offset:-512
	global_load_dword v204, v[10:11], off offset:-256
	global_load_dword v205, v[10:11], off
	v_lshl_add_u64 v[10:11], v[10:11], 0, s[20:21]
	global_load_dword v206, v[10:11], off offset:-1792
	global_load_dword v207, v[10:11], off offset:-1536
	global_load_dword v208, v[10:11], off offset:-1280
	global_load_dword v209, v[10:11], off offset:-1024
	global_load_dword v210, v[10:11], off offset:-768
	global_load_dword v211, v[10:11], off offset:-512
	global_load_dword v212, v[10:11], off offset:-256
	global_load_dword v213, v[10:11], off
	v_lshl_add_u64 v[10:11], v[10:11], 0, s[20:21]
	global_load_dword v214, v[10:11], off offset:-1792
	global_load_dword v215, v[10:11], off offset:-1536
	global_load_dword v216, v[10:11], off offset:-1280
	global_load_dword v217, v[10:11], off offset:-1024
	global_load_dword v218, v[10:11], off offset:-768
	global_load_dword v219, v[10:11], off offset:-512
	global_load_dword v220, v[10:11], off offset:-256
	global_load_dword v221, v[10:11], off
	v_lshl_add_u64 v[10:11], v[10:11], 0, s[20:21]
	global_load_dword v222, v[10:11], off offset:-1792
	global_load_dword v223, v[10:11], off offset:-1536
	global_load_dword v224, v[10:11], off offset:-1280
	global_load_dword v225, v[10:11], off offset:-1024
	global_load_dword v226, v[10:11], off offset:-768
	global_load_dword v227, v[10:11], off offset:-512
	global_load_dword v228, v[10:11], off offset:-256
	global_load_dword v229, v[10:11], off
	v_mov_b64_e32 v[10:11], v[4:5]
	global_load_dword v51, v[10:11], off offset:-2560
	global_load_dword v52, v[10:11], off offset:-2304
	global_load_dword v53, v[10:11], off offset:-2048
	global_load_dword v54, v[10:11], off offset:-1792
	global_load_dword v55, v[10:11], off offset:-1536
	global_load_dword v56, v[10:11], off offset:-1280
	global_load_dword v57, v[10:11], off offset:-1024
	global_load_dword v58, v[10:11], off offset:-768
	global_load_dword v59, v[10:11], off offset:-512
	global_load_dword v60, v[10:11], off offset:-256
	global_load_dword v61, v[10:11], off
	v_lshl_add_u64 v[10:11], v[10:11], 0, s[18:19]
	global_load_dword v62, v[10:11], off offset:-2560
	global_load_dword v63, v[10:11], off offset:-2304
	global_load_dword v64, v[10:11], off offset:-2048
	global_load_dword v65, v[10:11], off offset:-1792
	global_load_dword v66, v[10:11], off offset:-1536
	global_load_dword v67, v[10:11], off offset:-1280
	global_load_dword v68, v[10:11], off offset:-1024
	global_load_dword v69, v[10:11], off offset:-768
	global_load_dword v70, v[10:11], off offset:-512
	global_load_dword v71, v[10:11], off offset:-256
	global_load_dword v72, v[10:11], off
	v_lshl_add_u64 v[10:11], v[10:11], 0, s[18:19]
	global_load_dword v73, v[10:11], off offset:-2560
	global_load_dword v74, v[10:11], off offset:-2304
	global_load_dword v75, v[10:11], off offset:-2048
	global_load_dword v76, v[10:11], off offset:-1792
	global_load_dword v77, v[10:11], off offset:-1536
	global_load_dword v78, v[10:11], off offset:-1280
	global_load_dword v79, v[10:11], off offset:-1024
	global_load_dword v80, v[10:11], off offset:-768
	global_load_dword v81, v[10:11], off offset:-512
	global_load_dword v82, v[10:11], off offset:-256
	global_load_dword v83, v[10:11], off
	s_waitcnt vmcnt(0)
	s_branch .LBB0_210

; #define GAS __attribute__((address_space(1)))
; __device__ __forceinline__ void pro_a(Frame& F, CArgs a, unsigned long long& tm_acc) {
;     ...
;                 float h = ((const GAS float*)a->in[I_FB1])[l * 64 + F.lane];
;                 for (int i = 0; i < 33; ++i) h += __shfl(zf, i) * ((const GAS float*)a->in[I_FW1])[((size_t)l * 33 + i) * 64 + F.lane];
;                 h = sinf(((const GAS float*)a->in[I_FF1])[l * 64 + F.lane] * h);
.LBB0_228:
	s_or_b64 exec, exec, s[10:11]
	s_mov_b32 s10, 0
	v_mov_b64_e32 v[10:11], v[4:5]
	s_waitcnt vmcnt(5)
	v_mov_b32_e32 v28, v12
	v_add_u32_e32 v40, 0, v21
	ds_bpermute_b32 v41, v40, v2
	ds_bpermute_b32 v42, v40, v2 offset:4
	ds_bpermute_b32 v43, v40, v2 offset:8
	ds_bpermute_b32 v44, v40, v2 offset:12
	ds_bpermute_b32 v45, v40, v2 offset:16
	ds_bpermute_b32 v46, v40, v2 offset:20
	ds_bpermute_b32 v47, v40, v2 offset:24
	ds_bpermute_b32 v48, v40, v2 offset:28
	ds_bpermute_b32 v49, v40, v2 offset:32
	ds_bpermute_b32 v50, v40, v2 offset:36
	ds_bpermute_b32 v40, v40, v2 offset:40
	s_waitcnt lgkmcnt(10)
	v_fmac_f32_e32 v28, v51, v41
	s_waitcnt lgkmcnt(9)
	v_fmac_f32_e32 v28, v52, v42
	s_waitcnt lgkmcnt(8)
	v_fmac_f32_e32 v28, v53, v43
	s_waitcnt lgkmcnt(7)
	v_fmac_f32_e32 v28, v54, v44
	s_waitcnt lgkmcnt(6)
	v_fmac_f32_e32 v28, v55, v45
	s_waitcnt lgkmcnt(5)
	v_fmac_f32_e32 v28, v56, v46
	s_waitcnt lgkmcnt(4)
	v_fmac_f32_e32 v28, v57, v47
	s_waitcnt lgkmcnt(3)
	v_fmac_f32_e32 v28, v58, v48
	s_waitcnt lgkmcnt(2)
	v_fmac_f32_e32 v28, v59, v49
	s_waitcnt lgkmcnt(1)
	v_fmac_f32_e32 v28, v60, v50
	s_waitcnt lgkmcnt(0)
	v_fmac_f32_e32 v28, v61, v40
	v_add_u32_e32 v40, 44, v21
	ds_bpermute_b32 v41, v40, v2
	ds_bpermute_b32 v42, v40, v2 offset:4
	ds_bpermute_b32 v43, v40, v2 offset:8
	ds_bpermute_b32 v44, v40, v2 offset:12
	ds_bpermute_b32 v45, v40, v2 offset:16
	ds_bpermute_b32 v46, v40, v2 offset:20
	ds_bpermute_b32 v47, v40, v2 offset:24
	ds_bpermute_b32 v48, v40, v2 offset:28
	ds_bpermute_b32 v49, v40, v2 offset:32
	ds_bpermute_b32 v50, v40, v2 offset:36
	ds_bpermute_b32 v40, v40, v2 offset:40
	s_waitcnt lgkmcnt(10)
	v_fmac_f32_e32 v28, v62, v41
	s_waitcnt lgkmcnt(9)
	v_fmac_f32_e32 v28, v63, v42
	s_waitcnt lgkmcnt(8)
	v_fmac_f32_e32 v28, v64, v43
	s_waitcnt lgkmcnt(7)
	v_fmac_f32_e32 v28, v65, v44
	s_waitcnt lgkmcnt(6)
	v_fmac_f32_e32 v28, v66, v45
	s_waitcnt lgkmcnt(5)
	v_fmac_f32_e32 v28, v67, v46
	s_waitcnt lgkmcnt(4)
	v_fmac_f32_e32 v28, v68, v47
	s_waitcnt lgkmcnt(3)
	v_fmac_f32_e32 v28, v69, v48
	s_waitcnt lgkmcnt(2)
	v_fmac_f32_e32 v28, v70, v49
	s_waitcnt lgkmcnt(1)
	v_fmac_f32_e32 v28, v71, v50
	s_waitcnt lgkmcnt(0)
	v_fmac_f32_e32 v28, v72, v40
	v_add_u32_e32 v40, 0x58, v21
	ds_bpermute_b32 v41, v40, v2
	ds_bpermute_b32 v42, v40, v2 offset:4
	ds_bpermute_b32 v43, v40, v2 offset:8
	ds_bpermute_b32 v44, v40, v2 offset:12
	ds_bpermute_b32 v45, v40, v2 offset:16
	ds_bpermute_b32 v46, v40, v2 offset:20
	ds_bpermute_b32 v47, v40, v2 offset:24
	ds_bpermute_b32 v48, v40, v2 offset:28
	ds_bpermute_b32 v49, v40, v2 offset:32
	ds_bpermute_b32 v50, v40, v2 offset:36
	ds_bpermute_b32 v40, v40, v2 offset:40
	s_waitcnt lgkmcnt(10)
	v_fmac_f32_e32 v28, v73, v41
	s_waitcnt lgkmcnt(9)
	v_fmac_f32_e32 v28, v74, v42
	s_waitcnt lgkmcnt(8)
	v_fmac_f32_e32 v28, v75, v43
	s_waitcnt lgkmcnt(7)
	v_fmac_f32_e32 v28, v76, v44
	s_waitcnt lgkmcnt(6)
	v_fmac_f32_e32 v28, v77, v45
	s_waitcnt lgkmcnt(5)
	v_fmac_f32_e32 v28, v78, v46
	s_waitcnt lgkmcnt(4)
	v_fmac_f32_e32 v28, v79, v47
	s_waitcnt lgkmcnt(3)
	v_fmac_f32_e32 v28, v80, v48
	s_waitcnt lgkmcnt(2)
	v_fmac_f32_e32 v28, v81, v49
	s_waitcnt lgkmcnt(1)
	v_fmac_f32_e32 v28, v82, v50
	s_waitcnt lgkmcnt(0)
	v_fmac_f32_e32 v28, v83, v40
	v_mul_f32_e32 v10, v13, v28
	v_and_b32_e32 v11, 0x7fffffff, v10
	v_cmp_nlt_f32_e64 s[10:11], |v10|, s48
	s_and_saveexec_b64 s[12:13], s[10:11]
	s_xor_b64 s[22:23], exec, s[12:13]
	s_cbranch_execz .LBB0_232
	v_lshrrev_b32_e32 v2, 23, v11
	v_add_u32_e32 v2, 0xffffff88, v2
	v_cmp_lt_u32_e32 vcc, 63, v2
	s_nop 1
	v_cndmask_b32_e32 v28, 0, v24, vcc
	v_add_u32_e32 v2, v28, v2
	v_cmp_lt_u32_e64 s[10:11], 31, v2
	s_nop 1
	v_cndmask_b32_e64 v28, 0, v25, s[10:11]
	v_add_u32_e32 v2, v28, v2
	v_cmp_lt_u32_e64 s[12:13], 31, v2
	s_nop 1
	v_cndmask_b32_e64 v28, 0, v25, s[12:13]
	v_add_u32_e32 v42, v28, v2
	v_and_b32_e32 v2, 0x7fffff, v11
	v_or_b32_e32 v40, 0x800000, v2
	v_mad_u64_u32 v[28:29], s[14:15], v40, s49, 0
	v_mov_b32_e32 v2, v29
	v_mad_u64_u32 v[30:31], s[14:15], v40, s50, v[2:3]
	v_mov_b32_e32 v2, v31
	v_mad_u64_u32 v[32:33], s[14:15], v40, s51, v[2:3]
	v_mov_b32_e32 v2, v33
	v_mad_u64_u32 v[34:35], s[14:15], v40, s52, v[2:3]
	v_mov_b32_e32 v2, v35
	v_mad_u64_u32 v[36:37], s[14:15], v40, s53, v[2:3]
	v_mov_b32_e32 v2, v37
	v_mad_u64_u32 v[38:39], s[14:15], v40, s54, v[2:3]
	v_mov_b32_e32 v2, v39
	v_mad_u64_u32 v[40:41], s[14:15], v40, s55, v[2:3]
	v_cndmask_b32_e32 v29, v38, v34, vcc
	v_cndmask_b32_e32 v2, v40, v36, vcc
	v_cndmask_b32_e32 v33, v41, v38, vcc
	v_cndmask_b32_e64 v31, v2, v29, s[10:11]
	v_cndmask_b32_e64 v2, v33, v2, s[10:11]
	v_cndmask_b32_e32 v33, v36, v32, vcc
	v_cndmask_b32_e64 v29, v29, v33, s[10:11]
	v_cndmask_b32_e32 v30, v34, v30, vcc
	v_cndmask_b32_e64 v2, v2, v31, s[12:13]
	v_cndmask_b32_e64 v31, v31, v29, s[12:13]
	v_sub_u32_e32 v35, 32, v42
	v_cndmask_b32_e64 v33, v33, v30, s[10:11]
	v_alignbit_b32 v36, v2, v31, v35
	v_cmp_eq_u32_e64 s[14:15], 0, v42
	v_cndmask_b32_e64 v29, v29, v33, s[12:13]
	v_cndmask_b32_e32 v28, v32, v28, vcc
	v_cndmask_b32_e64 v2, v36, v2, s[14:15]
	v_alignbit_b32 v34, v31, v29, v35
	v_cndmask_b32_e64 v28, v30, v28, s[10:11]
	v_cndmask_b32_e64 v31, v34, v31, s[14:15]
	v_bfe_u32 v37, v2, 29, 1
	v_cndmask_b32_e64 v28, v33, v28, s[12:13]
	v_alignbit_b32 v34, v2, v31, 30
	v_sub_u32_e32 v38, 0, v37
	v_alignbit_b32 v30, v29, v28, v35
	v_xor_b32_e32 v34, v34, v38
	v_cndmask_b32_e64 v29, v30, v29, s[14:15]
	v_alignbit_b32 v30, v31, v29, 30
	v_ffbh_u32_e32 v31, v34
	v_min_u32_e32 v31, 32, v31
	v_alignbit_b32 v28, v29, v28, 30
	v_xor_b32_e32 v30, v30, v38
	v_sub_u32_e32 v32, 31, v31
	v_xor_b32_e32 v28, v28, v38
	v_alignbit_b32 v33, v34, v30, v32
	v_alignbit_b32 v28, v30, v28, v32
	v_alignbit_b32 v29, v33, v28, 9
	v_ffbh_u32_e32 v30, v29
	v_min_u32_e32 v30, 32, v30
	v_lshrrev_b32_e32 v36, 29, v2
	v_not_b32_e32 v32, v30
	v_alignbit_b32 v28, v29, v28, v32
	v_lshlrev_b32_e32 v29, 31, v36
	v_or_b32_e32 v32, 0x33000000, v29
	v_add_lshl_u32 v30, v30, v31, 23
	v_lshrrev_b32_e32 v28, 9, v28
	v_sub_u32_e32 v30, v32, v30
	v_or_b32_e32 v29, 0.5, v29
	v_lshlrev_b32_e32 v31, 23, v31
	v_or_b32_e32 v28, v30, v28
	v_lshrrev_b32_e32 v30, 9, v33
	v_sub_u32_e32 v29, v29, v31
	v_or_b32_e32 v29, v30, v29
	v_mul_f32_e32 v30, 0x3fc90fda, v29
	v_fma_f32 v31, v29, s56, -v30
	v_fmac_f32_e32 v31, 0x33a22168, v29
	v_fmac_f32_e32 v31, 0x3fc90fda, v28
	v_lshrrev_b32_e32 v2, 30, v2
	v_add_f32_e32 v28, v30, v31
	v_add_u32_e32 v2, v37, v2
